# combo + stolen weight-conversion rebalance: ph3 tail keeps only FFN1 gate/up and mix_in (it was steal-bound); FFN1 down to ph6 tail, FFN2 down to ph10 tail, FFN3 down to ph13 tail
# speedup vs baseline: 1.0027x; 1.0009x over previous
; __device__ __forceinline__ void convert_item(const Args& a, int it, LAS float* scr, int lane) {
;     ...
;         if (it < T_FFN) { const int m = it / 2752, r = it % 2752, f = m / 3, kind = m % 3;
;             if (kind < 2) { k0 = (r / 86) * 64; n0 = (r % 86) * 64; src = a.in[kind ? I_WU : I_WG] + (size_t)f * DM * DFF; ldn = DFF; Kd = DM; dst = WGU + (size_t)f * 2 * DFF * DM; drow = (n0 >> 7) * 256 + kind * 128 + (n0 & 127); }
;             else { k0 = (r / 32) * 64; n0 = (r % 32) * 64; src = a.in[I_WDN] + (size_t)f * DFF * DM; ldn = DM; Kd = DFF; dst = WD + (size_t)f * DM * DFF; drow = n0; }
;     ...
;     for (;;) {
;         __syncthreads();
;         if (tid == 0) bc[0] = (int)__hip_atomic_fetch_add(ctr, (unsigned)NSTEAL, __ATOMIC_RELAXED, __HIP_MEMORY_SCOPE_AGENT);
;         __syncthreads();
;         const int base = bc[0];
;         if (base >= n) break;
;         const int j = base + w;
;         if (w < NSTEAL && j < n) convert_item(a, j < n1 ? lo1 + j : (j < n1 + n2 ? lo2 + (j - n1) : lo3 + (j - n1 - n2)), scr, lane);
.LBB0_214:
	s_or_b64 exec, exec, s[8:9]
	v_mov_b32_e32 v1, s23
	s_waitcnt lgkmcnt(0)
	s_barrier
	ds_read_b32 v1, v1
	s_movk_i32 s8, 0x203f
	s_waitcnt lgkmcnt(0)
	v_cmp_lt_i32_e32 vcc, s8, v1
	v_readfirstlane_b32 s10, v1
	s_mov_b64 s[8:9], -1
	s_cbranch_vccnz .LBB0_209
	s_add_i32 s8, s10, s4
	s_cmpk_lt_i32 s8, 0x2040
	s_cselect_b64 s[10:11], -1, 0
	s_and_b64 s[10:11], s[6:7], s[10:11]
	s_andn2_b64 vcc, exec, s[10:11]
	s_cbranch_vccnz .LBB0_208
	s_cmpk_lt_i32 s8, 0x1580
	s_movk_i32 s9, 0x35c0
	s_cselect_b32 s9, s9, 0x35c0
	s_add_i32 s9, s9, s8
	s_mul_hi_i32 s8, s9, 0x2fa0be83
	s_lshr_b32 s10, s8, 31
	s_ashr_i32 s8, s8, 9
	s_add_i32 s8, s8, s10
	s_mul_i32 s10, s8, 0xac0
	s_sub_i32 s14, s9, s10
	s_mul_hi_i32 s9, s9, 0xfe03f81
	s_lshr_b32 s10, s9, 31
	s_ashr_i32 s26, s9, 9
	s_mul_hi_i32 s9, s8, 0x55555556
	s_add_i32 s26, s26, s10
	s_lshr_b32 s10, s9, 31
	s_add_i32 s9, s9, s10
	s_mul_i32 s9, s9, 3
	s_sub_i32 s13, s8, s9
	s_cmp_gt_i32 s13, 1
	s_mov_b64 s[8:9], -1
	s_sext_i32_i16 s18, s14
	s_mul_hi_i32 s15, s26, 0x2b00000
	s_mul_i32 s19, s26, 0x2b00000
	s_cbranch_scc0 .LBB0_218
	s_bfe_u32 s8, s18, 0x5001a
	s_add_i32 s8, s14, s8
	s_sext_i32_i16 s9, s8
	s_and_b32 s8, s8, 0xffe0
	s_sub_i32 s8, s14, s8
	s_sext_i32_i16 s8, s8
	v_readlane_b32 s64, v248, 11
	s_lshr_b32 s12, s9, 5
	s_lshl_b32 s25, s8, 6
	v_readlane_b32 s66, v248, 13
	v_readlane_b32 s67, v248, 14
	s_add_u32 s16, s66, s19
	s_addc_u32 s17, s67, s15
	s_mul_hi_i32 s8, s26, 0x1580000
	s_mul_i32 s26, s26, 0x1580000
	v_readlane_b32 s9, v248, 40
	s_add_u32 s10, s9, s26
	v_readlane_b32 s9, v248, 41
	v_readlane_b32 s65, v248, 12
	v_readlane_b32 s68, v248, 15
	v_readlane_b32 s69, v248, 16
	v_readlane_b32 s70, v248, 17
	v_readlane_b32 s71, v248, 18
	v_readlane_b32 s72, v248, 19
	v_readlane_b32 s73, v248, 20
	v_readlane_b32 s74, v248, 21
	v_readlane_b32 s75, v248, 22
	v_readlane_b32 s76, v248, 23
	v_readlane_b32 s77, v248, 24
	v_readlane_b32 s78, v248, 25
	v_readlane_b32 s79, v248, 26
	s_addc_u32 s11, s9, s8
	s_mov_b64 s[8:9], 0

; __device__ __forceinline__ void convert_item(const Args& a, int it, LAS float* scr, int lane) {
;     ...
;         if (it < T_FFN) { const int m = it / 2752, r = it % 2752, f = m / 3, kind = m % 3;
;             if (kind < 2) { k0 = (r / 86) * 64; n0 = (r % 86) * 64; src = a.in[kind ? I_WU : I_WG] + (size_t)f * DM * DFF; ldn = DFF; Kd = DM; dst = WGU + (size_t)f * 2 * DFF * DM; drow = (n0 >> 7) * 256 + kind * 128 + (n0 & 127); }
;             else { k0 = (r / 32) * 64; n0 = (r % 32) * 64; src = a.in[I_WDN] + (size_t)f * DFF * DM; ldn = DM; Kd = DFF; dst = WD + (size_t)f * DM * DFF; drow = n0; }
;     ...
;     for (;;) {
;         __syncthreads();
;         if (tid == 0) bc[0] = (int)__hip_atomic_fetch_add(ctr, (unsigned)NSTEAL, __ATOMIC_RELAXED, __HIP_MEMORY_SCOPE_AGENT);
;         __syncthreads();
;         const int base = bc[0];
;         if (base >= n) break;
;         const int j = base + w;
;         if (w < NSTEAL && j < n) convert_item(a, j < n1 ? lo1 + j : (j < n1 + n2 ? lo2 + (j - n1) : lo3 + (j - n1 - n2)), scr, lane);
.LBB0_372:
	s_or_b64 exec, exec, s[10:11]
	v_mov_b32_e32 v1, s23
	s_waitcnt lgkmcnt(0)
	s_barrier
	ds_read_b32 v1, v1
	s_movk_i32 s10, 0x2580
	s_waitcnt lgkmcnt(0)
	v_cmp_gt_i32_e32 vcc, s10, v1
	v_readfirstlane_b32 s12, v1
	s_mov_b64 s[10:11], -1
	s_cbranch_vccz .LBB0_367
	s_add_i32 s12, s12, s4
	s_cmpk_lt_i32 s12, 0x2580
	s_cselect_b64 s[10:11], -1, 0
	s_and_b64 s[10:11], s[8:9], s[10:11]
	s_andn2_b64 vcc, exec, s[10:11]
	s_cbranch_vccnz .LBB0_366
	s_cmpk_lt_u32 s12, 0x2b00
	s_movk_i32 s10, 0x6b80
	s_cselect_b32 s10, s10, 0x6b80
	s_cmpk_gt_i32 s12, 0x157f
	s_cselect_b32 s10, s10, 0x2040
	s_add_i32 s12, s12, s10
	s_cmp_gt_i32 s12, 0x80ff
	s_mov_b64 s[10:11], -1
	s_cbranch_scc0 .LBB0_376
	s_add_i32 s10, s12, 0xffff7f00
	v_readlane_b32 s64, v248, 11
	s_lshr_b32 s10, s10, 1
	v_readlane_b32 s74, v248, 21
	v_readlane_b32 s75, v248, 22
	s_and_b32 s14, s10, 0x7fffffc0
	s_lshl_b32 s10, s12, 6
	v_readlane_b32 s68, v248, 15
	v_readlane_b32 s69, v248, 16
	v_readlane_b32 s76, v248, 23
	v_readlane_b32 s77, v248, 24
	v_readlane_b32 s79, v248, 26
	s_movk_i32 s74, 0x8000
	s_and_b32 s26, s10, 0x1fc0
	s_mov_b64 s[10:11], 0
	v_readlane_b32 s65, v248, 12
	v_readlane_b32 s66, v248, 13
	v_readlane_b32 s67, v248, 14
	v_readlane_b32 s70, v248, 17
	v_readlane_b32 s71, v248, 18
	v_readlane_b32 s72, v248, 19
	v_readlane_b32 s73, v248, 20
	v_readlane_b32 s78, v248, 25
	s_mov_b64 s[76:77], 0x800
	s_mov_b32 s75, -1
	s_mov_b32 s79, 0x800000
	s_mov_b64 s[18:19], s[68:69]

; __device__ __forceinline__ void convert_item(const Args& a, int it, LAS float* scr, int lane) {
;     ...
;         if (it < T_FFN) { const int m = it / 2752, r = it % 2752, f = m / 3, kind = m % 3;
;             if (kind < 2) { k0 = (r / 86) * 64; n0 = (r % 86) * 64; src = a.in[kind ? I_WU : I_WG] + (size_t)f * DM * DFF; ldn = DFF; Kd = DM; dst = WGU + (size_t)f * 2 * DFF * DM; drow = (n0 >> 7) * 256 + kind * 128 + (n0 & 127); }
;             else { k0 = (r / 32) * 64; n0 = (r % 32) * 64; src = a.in[I_WDN] + (size_t)f * DFF * DM; ldn = DM; Kd = DFF; dst = WD + (size_t)f * DM * DFF; drow = n0; }
;     ...
;         __syncthreads();
;         const int base = bc[0];
;         if (base >= n) break;
;         const int j = base + w;
;         if (w < NSTEAL && j < n) convert_item(a, j < n1 ? lo1 + j : (j < n1 + n2 ? lo2 + (j - n1) : lo3 + (j - n1 - n2)), scr, lane);
.LBB0_454:
	s_or_b64 exec, exec, s[10:11]
	v_mov_b32_e32 v1, s23
	s_waitcnt lgkmcnt(0)
	s_barrier
	ds_read_b32 v1, v1
	s_movk_i32 s10, 0x157f
	s_waitcnt lgkmcnt(0)
	v_cmp_lt_i32_e32 vcc, s10, v1
	v_readfirstlane_b32 s12, v1
	s_mov_b64 s[10:11], -1
	s_cbranch_vccnz .LBB0_449
	s_add_i32 s10, s12, s4
	s_cmpk_lt_i32 s10, 0x1580
	s_cselect_b64 s[12:13], -1, 0
	s_and_b64 s[12:13], s[8:9], s[12:13]
	s_andn2_b64 vcc, exec, s[12:13]
	s_cbranch_vccnz .LBB0_448
	s_addk_i32 s10, 0x6b80
	s_mul_hi_i32 s11, s10, 0x2fa0be83
	s_lshr_b32 s12, s11, 31
	s_ashr_i32 s11, s11, 9
	s_add_i32 s11, s11, s12
	s_mul_i32 s12, s11, 0xac0
	s_sub_i32 s16, s10, s12
	s_mul_hi_i32 s10, s10, 0xfe03f81
	s_lshr_b32 s12, s10, 31
	s_ashr_i32 s28, s10, 9
	s_mul_hi_i32 s10, s11, 0x55555556
	s_add_i32 s28, s28, s12
	s_lshr_b32 s12, s10, 31
	s_add_i32 s10, s10, s12
	s_mul_i32 s10, s10, 3
	s_sub_i32 s15, s11, s10
	s_cmp_gt_i32 s15, 1
	s_mov_b64 s[10:11], -1
	s_sext_i32_i16 s26, s16
	s_mul_hi_i32 s17, s28, 0x2b00000
	s_mul_i32 s27, s28, 0x2b00000
	s_cbranch_scc0 .LBB0_458
	s_bfe_u32 s10, s26, 0x5001a
	s_add_i32 s10, s16, s10
	s_sext_i32_i16 s11, s10
	s_and_b32 s10, s10, 0xffe0
	s_sub_i32 s10, s16, s10
	s_sext_i32_i16 s10, s10
	v_readlane_b32 s64, v248, 11
	s_lshr_b32 s14, s11, 5
	s_lshl_b32 s25, s10, 6
	v_readlane_b32 s66, v248, 13
	v_readlane_b32 s67, v248, 14
	s_add_u32 s18, s66, s27
	s_addc_u32 s19, s67, s17
	s_mul_hi_i32 s10, s28, 0x1580000
	s_mul_i32 s28, s28, 0x1580000
	v_readlane_b32 s11, v248, 40
	s_add_u32 s12, s11, s28
	v_readlane_b32 s11, v248, 41
	v_readlane_b32 s65, v248, 12
	v_readlane_b32 s68, v248, 15
	v_readlane_b32 s69, v248, 16
	v_readlane_b32 s70, v248, 17
	v_readlane_b32 s71, v248, 18
	v_readlane_b32 s72, v248, 19
	v_readlane_b32 s73, v248, 20
	v_readlane_b32 s74, v248, 21
	v_readlane_b32 s75, v248, 22
	v_readlane_b32 s76, v248, 23
	v_readlane_b32 s77, v248, 24
	v_readlane_b32 s78, v248, 25
	v_readlane_b32 s79, v248, 26
	s_addc_u32 s13, s11, s10
	s_mov_b64 s[10:11], 0
